# v041 + NA loop back-edge rotation: counter/test/bias-pointer update moved before the closing barrier
# speedup vs baseline: 1.0013x; 1.0013x over previous
; #define A_DMAV(t, slot) do { const unsigned tt_ = (unsigned)((t) < NT ? (t) : NT - 1); \
;         glds16(dv_src[0] + (size_t)tt_ * 128u, (unsigned)__builtin_amdgcn_readfirstlane(lds_u + A_V0 + (slot) * A_VB + wid * 1024)); \
;         if (wid == 0) glds16(dv_src[1] + (size_t)tt_ * 128u, (unsigned)__builtin_amdgcn_readfirstlane(lds_u + A_V0 + (slot) * A_VB + 8 * 1024)); } while (0)
; template <bool NA>
; __device__ __forceinline__ void attn_unit(LAS unsigned char* lds, const bf16_t* Q, const bf16_t* Kg, const bf16_t* Kr, const bf16_t* Vt, bf16_t* O,
;                                           int h, int seqrow0, int q0, int t0, int NT, int rows, int g0, const float* rpb_h, int wid) {
;     ...
;     { A_DMAK(0, 0); A_DMAV(0, 0); A_DMAK(1, 1); A_DMAK(2, 2); A_DMAV(1, 1); }
;     asm volatile("s_waitcnt vmcnt(0)" ::: "memory");
;     __syncthreads();
;     f32x16 sA0, sA1, sB0, sB1; float tmA, tmB;
;     A_QK(sA0, sA1, 0);
;     A_MASK(sA0, sA1, 0);
;     tmA = rowmax32(sA0, sA1);
;     __syncthreads();
;     if constexpr (NA) {
;         for (int t = 0; t < NT; t += 2) {
;             A_STEP_NA(sA0, sA1, tmA, sB0, sB1, tmB, t);
;             if (t + 1 < NT) A_STEP_NA(sB0, sB1, tmB, sA0, sA1, tmA, t + 1);
.LBB0_865:
	s_add_i32 s1, s1, 2
	s_cmp_gt_i32 s85, s81
	v_add_u32_e32 v179, 0xf8, v179
	s_waitcnt vmcnt(0)
	s_barrier
	s_cbranch_scc0 .LBB0_768
	s_branch .LBB0_867
